# token-shift: both 8-row batches loaded up front
# baseline (speedup 1.0000x reference)
; __device__ __forceinline__ float lo16(unsigned w) { return __uint_as_float(w << 16); }
; __device__ __forceinline__ float hi16(unsigned w) { return __uint_as_float(w & 0xffff0000u); }
; __device__ void phase_prep(const Ctx& p, int l, LAS unsigned char* lds) {
;     ...
;             for (int r8 = 0; r8 < 16; r8 += 8) {
;             u32x4 wrow[8];
; #pragma unroll
;             for (int r = 0; r < 8; ++r) wrow[r] = *(const u32x4*)(PR + (size_t)(t0 + rstart + r8 + r) * 2048 + c0);
; #pragma unroll
;             for (int rr = 0; rr < 8; ++rr) {
;                 const int r = r8 + rr; const u32x4 w = wrow[rr];
;                 float cur[8], o[8];
;                 cur[0] = lo16(w.x); cur[1] = hi16(w.x); cur[2] = lo16(w.y); cur[3] = hi16(w.y); cur[4] = lo16(w.z); cur[5] = hi16(w.z); cur[6] = lo16(w.w); cur[7] = hi16(w.w);
.LBB0_619:
	s_mov_b64 s[60:61], exec
	v_cmp_eq_u32_e64 s[62:63], 1, v162
	v_cmp_eq_u32_e64 s[64:65], 2, v162
	s_mov_b64 s[14:15], 0x1000
	s_cmp_lg_u32 s10, 0
	s_cbranch_scc1 .Lshift_it2
	v_or_b32_e32 v216, s10, v48
	v_mov_b32_e32 v217, 0
	v_lshlrev_b64 v[218:219], 12, v[216:217]
	v_lshl_add_u64 v[218:219], v[88:89], 0, v[218:219]
	global_load_dwordx4 v[44:47], v[218:219], off
	v_lshl_add_u64 v[218:219], v[218:219], 0, s[14:15]
	global_load_dwordx4 v[32:35], v[218:219], off
	v_lshl_add_u64 v[218:219], v[218:219], 0, s[14:15]
	global_load_dwordx4 v[28:31], v[218:219], off
	v_lshl_add_u64 v[218:219], v[218:219], 0, s[14:15]
	global_load_dwordx4 v[24:27], v[218:219], off
	v_lshl_add_u64 v[218:219], v[218:219], 0, s[14:15]
	global_load_dwordx4 v[20:23], v[218:219], off
	v_lshl_add_u64 v[218:219], v[218:219], 0, s[14:15]
	global_load_dwordx4 v[16:19], v[218:219], off
	v_lshl_add_u64 v[218:219], v[218:219], 0, s[14:15]
	global_load_dwordx4 v[12:15], v[218:219], off
	v_lshl_add_u64 v[218:219], v[218:219], 0, s[14:15]
	global_load_dwordx4 v[8:11], v[218:219], off
	v_lshl_add_u64 v[218:219], v[218:219], 0, s[14:15]
	global_load_dwordx4 v[52:55], v[218:219], off
	v_lshl_add_u64 v[218:219], v[218:219], 0, s[14:15]
	global_load_dwordx4 v[56:59], v[218:219], off
	v_lshl_add_u64 v[218:219], v[218:219], 0, s[14:15]
	global_load_dwordx4 v[60:63], v[218:219], off
	v_lshl_add_u64 v[218:219], v[218:219], 0, s[14:15]
	global_load_dwordx4 v[64:67], v[218:219], off
	v_lshl_add_u64 v[218:219], v[218:219], 0, s[14:15]
	global_load_dwordx4 v[68:71], v[218:219], off
	v_lshl_add_u64 v[218:219], v[218:219], 0, s[14:15]
	global_load_dwordx4 v[72:75], v[218:219], off
	v_lshl_add_u64 v[218:219], v[218:219], 0, s[14:15]
	global_load_dwordx4 v[76:79], v[218:219], off
	v_lshl_add_u64 v[218:219], v[218:219], 0, s[14:15]
	global_load_dwordx4 v[80:83], v[218:219], off
	s_branch .Lshift_go
.Lshift_it2:
	s_waitcnt vmcnt(0)
	v_mov_b64_e32 v[44:45], v[52:53]
	v_mov_b64_e32 v[46:47], v[54:55]
	v_mov_b64_e32 v[32:33], v[56:57]
	v_mov_b64_e32 v[34:35], v[58:59]
	v_mov_b64_e32 v[28:29], v[60:61]
	v_mov_b64_e32 v[30:31], v[62:63]
	v_mov_b64_e32 v[24:25], v[64:65]
	v_mov_b64_e32 v[26:27], v[66:67]
	v_mov_b64_e32 v[20:21], v[68:69]
	v_mov_b64_e32 v[22:23], v[70:71]
	v_mov_b64_e32 v[16:17], v[72:73]
	v_mov_b64_e32 v[18:19], v[74:75]
	v_mov_b64_e32 v[12:13], v[76:77]
	v_mov_b64_e32 v[14:15], v[78:79]
	v_mov_b64_e32 v[8:9], v[80:81]
	v_mov_b64_e32 v[10:11], v[82:83]
.Lshift_go:
	v_or_b32_e32 v220, s10, v160
	v_mul_lo_u32 v220, v220, s75
	v_add_u32_e32 v220, v163, v220
	s_waitcnt vmcnt(15)
	s_cmp_lg_u32 s10, 0
	s_cbranch_scc1 .Lshift_pv
	v_cmp_eq_u32_e32 vcc, 1, v226
	s_nop 1
	s_and_saveexec_b64 s[16:17], vcc
	v_lshlrev_b32_e32 v40, 16, v222
	v_and_b32_e32 v41, 0xffff0000, v222
	v_lshlrev_b32_e32 v42, 16, v223
	v_and_b32_e32 v43, 0xffff0000, v223
	v_lshlrev_b32_e32 v36, 16, v224
	v_and_b32_e32 v37, 0xffff0000, v224
	v_lshlrev_b32_e32 v38, 16, v225
	v_and_b32_e32 v39, 0xffff0000, v225
	s_mov_b64 exec, s[16:17]

; __device__ __forceinline__ unsigned cvt_pk_bf16(float lo, float hi) { const f32x2_cv v = {lo, hi}; const bf16x2_cv b = __builtin_convertvector(v, bf16x2_cv); return __builtin_bit_cast(unsigned, b); }
; __device__ __forceinline__ float sigm(float x) { return __builtin_amdgcn_rcpf(1.0f + __expf(-x)); }
; __device__ __forceinline__ float tanh_fast(float x) { return 1.0f - 2.0f * __builtin_amdgcn_rcpf(1.0f + __expf(2.0f * x)); }
; __device__ __forceinline__ float lo16(unsigned w) { return __uint_as_float(w << 16); }
; __device__ __forceinline__ float hi16(unsigned w) { return __uint_as_float(w & 0xffff0000u); }
; __device__ void phase_prep(const Ctx& p, int l, LAS unsigned char* lds) {
;     ...
;             for (int rr = 0; rr < 8; ++rr) {
;                 const int r = r8 + rr; const u32x4 w = wrow[rr];
;                 float cur[8], o[8];
;                 cur[0] = lo16(w.x); cur[1] = hi16(w.x); cur[2] = lo16(w.y); cur[3] = hi16(w.y); cur[4] = lo16(w.z); cur[5] = hi16(w.z); cur[6] = lo16(w.w); cur[7] = hi16(w.w);
; #pragma unroll
;                 for (int j = 0; j < 8; ++j) { float x = cur[j] + (prev[j] - cur[j]) * m8[j]; if (fn == 1) x = tanh_fast(x); else if (fn == 2) x = sigm(x); o[j] = x; prev[j] = cur[j]; }
;                 u32x4 q; q.x = cvt_pk_bf16(o[0], o[1]); q.y = cvt_pk_bf16(o[2], o[3]); q.z = cvt_pk_bf16(o[4], o[5]); q.w = cvt_pk_bf16(o[6], o[7]);
;                 *(LAS u32x4*)(MX + (rstart + r) * MXS + c0) = q;
.Lshift_ns0:
	s_nop 0
	v_cvt_pk_bf16_f32 v212, v40, v41
	v_cvt_pk_bf16_f32 v213, v42, v43
	v_cvt_pk_bf16_f32 v214, v36, v37
	v_cvt_pk_bf16_f32 v215, v38, v39
	ds_write_b128 v220, v[212:215]
	s_waitcnt vmcnt(14)
	v_lshlrev_b32_e32 v204, 16, v32
	v_and_b32_e32 v205, 0xffff0000, v32
	v_lshlrev_b32_e32 v206, 16, v33
	v_and_b32_e32 v207, 0xffff0000, v33
	v_lshlrev_b32_e32 v208, 16, v34
	v_and_b32_e32 v209, 0xffff0000, v34
	v_lshlrev_b32_e32 v210, 16, v35
	v_and_b32_e32 v211, 0xffff0000, v35
	v_sub_f32_e32 v196, v196, v204
	v_sub_f32_e32 v197, v197, v205
	v_sub_f32_e32 v198, v198, v206
	v_sub_f32_e32 v199, v199, v207
	v_sub_f32_e32 v200, v200, v208
	v_sub_f32_e32 v201, v201, v209
	v_sub_f32_e32 v202, v202, v210
	v_sub_f32_e32 v203, v203, v211
	v_fma_f32 v196, v4, v196, v204
	v_fma_f32 v197, v5, v197, v205
	v_fma_f32 v198, v6, v198, v206
	v_fma_f32 v199, v7, v199, v207
	v_fma_f32 v200, v0, v200, v208
	v_fma_f32 v201, v1, v201, v209
	v_fma_f32 v202, v2, v202, v210
	v_fma_f32 v203, v3, v203, v211
	s_cmp_lg_u64 s[62:63], 0
	s_cbranch_scc0 .Lshift_nt1
	s_mov_b64 exec, s[62:63]
	v_add_f32_e32 v196, v196, v196
	v_add_f32_e32 v197, v197, v197
	v_add_f32_e32 v198, v198, v198
	v_add_f32_e32 v199, v199, v199
	v_add_f32_e32 v200, v200, v200
	v_add_f32_e32 v201, v201, v201
	v_add_f32_e32 v202, v202, v202
	v_add_f32_e32 v203, v203, v203
	v_mul_f32_e32 v196, 0x3fb8aa3b, v196
	v_mul_f32_e32 v197, 0x3fb8aa3b, v197
	v_mul_f32_e32 v198, 0x3fb8aa3b, v198
	v_mul_f32_e32 v199, 0x3fb8aa3b, v199
	v_mul_f32_e32 v200, 0x3fb8aa3b, v200
	v_mul_f32_e32 v201, 0x3fb8aa3b, v201
	v_mul_f32_e32 v202, 0x3fb8aa3b, v202
	v_mul_f32_e32 v203, 0x3fb8aa3b, v203
	v_exp_f32_e32 v196, v196
	v_exp_f32_e32 v197, v197
	v_exp_f32_e32 v198, v198
	v_exp_f32_e32 v199, v199
	v_exp_f32_e32 v200, v200
	v_exp_f32_e32 v201, v201
	v_exp_f32_e32 v202, v202
	v_exp_f32_e32 v203, v203
	v_add_f32_e32 v196, 1.0, v196
	v_add_f32_e32 v197, 1.0, v197
	v_add_f32_e32 v198, 1.0, v198
	v_add_f32_e32 v199, 1.0, v199
	v_add_f32_e32 v200, 1.0, v200
	v_add_f32_e32 v201, 1.0, v201
	v_add_f32_e32 v202, 1.0, v202
	v_add_f32_e32 v203, 1.0, v203
	v_rcp_f32_e32 v196, v196
	v_rcp_f32_e32 v197, v197
	v_rcp_f32_e32 v198, v198
	v_rcp_f32_e32 v199, v199
	v_rcp_f32_e32 v200, v200
	v_rcp_f32_e32 v201, v201
	v_rcp_f32_e32 v202, v202
	v_rcp_f32_e32 v203, v203
	v_fma_f32 v196, v196, -2.0, 1.0
	v_fma_f32 v197, v197, -2.0, 1.0
	v_fma_f32 v198, v198, -2.0, 1.0
	v_fma_f32 v199, v199, -2.0, 1.0
	v_fma_f32 v200, v200, -2.0, 1.0
	v_fma_f32 v201, v201, -2.0, 1.0
	v_fma_f32 v202, v202, -2.0, 1.0
	v_fma_f32 v203, v203, -2.0, 1.0
	s_mov_b64 exec, s[60:61]

; __device__ __forceinline__ unsigned cvt_pk_bf16(float lo, float hi) { const f32x2_cv v = {lo, hi}; const bf16x2_cv b = __builtin_convertvector(v, bf16x2_cv); return __builtin_bit_cast(unsigned, b); }
; __device__ __forceinline__ float sigm(float x) { return __builtin_amdgcn_rcpf(1.0f + __expf(-x)); }
; __device__ __forceinline__ float tanh_fast(float x) { return 1.0f - 2.0f * __builtin_amdgcn_rcpf(1.0f + __expf(2.0f * x)); }
; __device__ __forceinline__ float lo16(unsigned w) { return __uint_as_float(w << 16); }
; __device__ __forceinline__ float hi16(unsigned w) { return __uint_as_float(w & 0xffff0000u); }
; __device__ void phase_prep(const Ctx& p, int l, LAS unsigned char* lds) {
;     ...
;             for (int rr = 0; rr < 8; ++rr) {
;                 const int r = r8 + rr; const u32x4 w = wrow[rr];
;                 float cur[8], o[8];
;                 cur[0] = lo16(w.x); cur[1] = hi16(w.x); cur[2] = lo16(w.y); cur[3] = hi16(w.y); cur[4] = lo16(w.z); cur[5] = hi16(w.z); cur[6] = lo16(w.w); cur[7] = hi16(w.w);
; #pragma unroll
;                 for (int j = 0; j < 8; ++j) { float x = cur[j] + (prev[j] - cur[j]) * m8[j]; if (fn == 1) x = tanh_fast(x); else if (fn == 2) x = sigm(x); o[j] = x; prev[j] = cur[j]; }
;                 u32x4 q; q.x = cvt_pk_bf16(o[0], o[1]); q.y = cvt_pk_bf16(o[2], o[3]); q.z = cvt_pk_bf16(o[4], o[5]); q.w = cvt_pk_bf16(o[6], o[7]);
;                 *(LAS u32x4*)(MX + (rstart + r) * MXS + c0) = q;
.Lshift_ns1:
	s_nop 0
	v_cvt_pk_bf16_f32 v212, v196, v197
	v_cvt_pk_bf16_f32 v213, v198, v199
	v_cvt_pk_bf16_f32 v214, v200, v201
	v_cvt_pk_bf16_f32 v215, v202, v203
	ds_write_b128 v220, v[212:215] offset:3664
	s_waitcnt vmcnt(13)
	v_lshlrev_b32_e32 v196, 16, v28
	v_and_b32_e32 v197, 0xffff0000, v28
	v_lshlrev_b32_e32 v198, 16, v29
	v_and_b32_e32 v199, 0xffff0000, v29
	v_lshlrev_b32_e32 v200, 16, v30
	v_and_b32_e32 v201, 0xffff0000, v30
	v_lshlrev_b32_e32 v202, 16, v31
	v_and_b32_e32 v203, 0xffff0000, v31
	v_sub_f32_e32 v204, v204, v196
	v_sub_f32_e32 v205, v205, v197
	v_sub_f32_e32 v206, v206, v198
	v_sub_f32_e32 v207, v207, v199
	v_sub_f32_e32 v208, v208, v200
	v_sub_f32_e32 v209, v209, v201
	v_sub_f32_e32 v210, v210, v202
	v_sub_f32_e32 v211, v211, v203
	v_fma_f32 v204, v4, v204, v196
	v_fma_f32 v205, v5, v205, v197
	v_fma_f32 v206, v6, v206, v198
	v_fma_f32 v207, v7, v207, v199
	v_fma_f32 v208, v0, v208, v200
	v_fma_f32 v209, v1, v209, v201
	v_fma_f32 v210, v2, v210, v202
	v_fma_f32 v211, v3, v211, v203
	s_cmp_lg_u64 s[62:63], 0
	s_cbranch_scc0 .Lshift_nt2
	s_mov_b64 exec, s[62:63]
	v_add_f32_e32 v204, v204, v204
	v_add_f32_e32 v205, v205, v205
	v_add_f32_e32 v206, v206, v206
	v_add_f32_e32 v207, v207, v207
	v_add_f32_e32 v208, v208, v208
	v_add_f32_e32 v209, v209, v209
	v_add_f32_e32 v210, v210, v210
	v_add_f32_e32 v211, v211, v211
	v_mul_f32_e32 v204, 0x3fb8aa3b, v204
	v_mul_f32_e32 v205, 0x3fb8aa3b, v205
	v_mul_f32_e32 v206, 0x3fb8aa3b, v206
	v_mul_f32_e32 v207, 0x3fb8aa3b, v207
	v_mul_f32_e32 v208, 0x3fb8aa3b, v208
	v_mul_f32_e32 v209, 0x3fb8aa3b, v209
	v_mul_f32_e32 v210, 0x3fb8aa3b, v210
	v_mul_f32_e32 v211, 0x3fb8aa3b, v211
	v_exp_f32_e32 v204, v204
	v_exp_f32_e32 v205, v205
	v_exp_f32_e32 v206, v206
	v_exp_f32_e32 v207, v207
	v_exp_f32_e32 v208, v208
	v_exp_f32_e32 v209, v209
	v_exp_f32_e32 v210, v210
	v_exp_f32_e32 v211, v211
	v_add_f32_e32 v204, 1.0, v204
	v_add_f32_e32 v205, 1.0, v205
	v_add_f32_e32 v206, 1.0, v206
	v_add_f32_e32 v207, 1.0, v207
	v_add_f32_e32 v208, 1.0, v208
	v_add_f32_e32 v209, 1.0, v209
	v_add_f32_e32 v210, 1.0, v210
	v_add_f32_e32 v211, 1.0, v211
	v_rcp_f32_e32 v204, v204
	v_rcp_f32_e32 v205, v205
	v_rcp_f32_e32 v206, v206
	v_rcp_f32_e32 v207, v207
	v_rcp_f32_e32 v208, v208
	v_rcp_f32_e32 v209, v209
	v_rcp_f32_e32 v210, v210
	v_rcp_f32_e32 v211, v211
	v_fma_f32 v204, v204, -2.0, 1.0
	v_fma_f32 v205, v205, -2.0, 1.0
	v_fma_f32 v206, v206, -2.0, 1.0
	v_fma_f32 v207, v207, -2.0, 1.0
	v_fma_f32 v208, v208, -2.0, 1.0
	v_fma_f32 v209, v209, -2.0, 1.0
	v_fma_f32 v210, v210, -2.0, 1.0
	v_fma_f32 v211, v211, -2.0, 1.0
	s_mov_b64 exec, s[60:61]

; __device__ __forceinline__ unsigned cvt_pk_bf16(float lo, float hi) { const f32x2_cv v = {lo, hi}; const bf16x2_cv b = __builtin_convertvector(v, bf16x2_cv); return __builtin_bit_cast(unsigned, b); }
; __device__ __forceinline__ float sigm(float x) { return __builtin_amdgcn_rcpf(1.0f + __expf(-x)); }
; __device__ __forceinline__ float tanh_fast(float x) { return 1.0f - 2.0f * __builtin_amdgcn_rcpf(1.0f + __expf(2.0f * x)); }
; __device__ __forceinline__ float lo16(unsigned w) { return __uint_as_float(w << 16); }
; __device__ __forceinline__ float hi16(unsigned w) { return __uint_as_float(w & 0xffff0000u); }
; __device__ void phase_prep(const Ctx& p, int l, LAS unsigned char* lds) {
;     ...
;             for (int rr = 0; rr < 8; ++rr) {
;                 const int r = r8 + rr; const u32x4 w = wrow[rr];
;                 float cur[8], o[8];
;                 cur[0] = lo16(w.x); cur[1] = hi16(w.x); cur[2] = lo16(w.y); cur[3] = hi16(w.y); cur[4] = lo16(w.z); cur[5] = hi16(w.z); cur[6] = lo16(w.w); cur[7] = hi16(w.w);
; #pragma unroll
;                 for (int j = 0; j < 8; ++j) { float x = cur[j] + (prev[j] - cur[j]) * m8[j]; if (fn == 1) x = tanh_fast(x); else if (fn == 2) x = sigm(x); o[j] = x; prev[j] = cur[j]; }
;                 u32x4 q; q.x = cvt_pk_bf16(o[0], o[1]); q.y = cvt_pk_bf16(o[2], o[3]); q.z = cvt_pk_bf16(o[4], o[5]); q.w = cvt_pk_bf16(o[6], o[7]);
;                 *(LAS u32x4*)(MX + (rstart + r) * MXS + c0) = q;
.Lshift_ns2:
	s_nop 0
	v_cvt_pk_bf16_f32 v212, v204, v205
	v_cvt_pk_bf16_f32 v213, v206, v207
	v_cvt_pk_bf16_f32 v214, v208, v209
	v_cvt_pk_bf16_f32 v215, v210, v211
	ds_write_b128 v220, v[212:215] offset:7328
	s_waitcnt vmcnt(12)
	v_lshlrev_b32_e32 v204, 16, v24
	v_and_b32_e32 v205, 0xffff0000, v24
	v_lshlrev_b32_e32 v206, 16, v25
	v_and_b32_e32 v207, 0xffff0000, v25
	v_lshlrev_b32_e32 v208, 16, v26
	v_and_b32_e32 v209, 0xffff0000, v26
	v_lshlrev_b32_e32 v210, 16, v27
	v_and_b32_e32 v211, 0xffff0000, v27
	v_sub_f32_e32 v196, v196, v204
	v_sub_f32_e32 v197, v197, v205
	v_sub_f32_e32 v198, v198, v206
	v_sub_f32_e32 v199, v199, v207
	v_sub_f32_e32 v200, v200, v208
	v_sub_f32_e32 v201, v201, v209
	v_sub_f32_e32 v202, v202, v210
	v_sub_f32_e32 v203, v203, v211
	v_fma_f32 v196, v4, v196, v204
	v_fma_f32 v197, v5, v197, v205
	v_fma_f32 v198, v6, v198, v206
	v_fma_f32 v199, v7, v199, v207
	v_fma_f32 v200, v0, v200, v208
	v_fma_f32 v201, v1, v201, v209
	v_fma_f32 v202, v2, v202, v210
	v_fma_f32 v203, v3, v203, v211
	s_cmp_lg_u64 s[62:63], 0
	s_cbranch_scc0 .Lshift_nt3
	s_mov_b64 exec, s[62:63]
	v_add_f32_e32 v196, v196, v196
	v_add_f32_e32 v197, v197, v197
	v_add_f32_e32 v198, v198, v198
	v_add_f32_e32 v199, v199, v199
	v_add_f32_e32 v200, v200, v200
	v_add_f32_e32 v201, v201, v201
	v_add_f32_e32 v202, v202, v202
	v_add_f32_e32 v203, v203, v203
	v_mul_f32_e32 v196, 0x3fb8aa3b, v196
	v_mul_f32_e32 v197, 0x3fb8aa3b, v197
	v_mul_f32_e32 v198, 0x3fb8aa3b, v198
	v_mul_f32_e32 v199, 0x3fb8aa3b, v199
	v_mul_f32_e32 v200, 0x3fb8aa3b, v200
	v_mul_f32_e32 v201, 0x3fb8aa3b, v201
	v_mul_f32_e32 v202, 0x3fb8aa3b, v202
	v_mul_f32_e32 v203, 0x3fb8aa3b, v203
	v_exp_f32_e32 v196, v196
	v_exp_f32_e32 v197, v197
	v_exp_f32_e32 v198, v198
	v_exp_f32_e32 v199, v199
	v_exp_f32_e32 v200, v200
	v_exp_f32_e32 v201, v201
	v_exp_f32_e32 v202, v202
	v_exp_f32_e32 v203, v203
	v_add_f32_e32 v196, 1.0, v196
	v_add_f32_e32 v197, 1.0, v197
	v_add_f32_e32 v198, 1.0, v198
	v_add_f32_e32 v199, 1.0, v199
	v_add_f32_e32 v200, 1.0, v200
	v_add_f32_e32 v201, 1.0, v201
	v_add_f32_e32 v202, 1.0, v202
	v_add_f32_e32 v203, 1.0, v203
	v_rcp_f32_e32 v196, v196
	v_rcp_f32_e32 v197, v197
	v_rcp_f32_e32 v198, v198
	v_rcp_f32_e32 v199, v199
	v_rcp_f32_e32 v200, v200
	v_rcp_f32_e32 v201, v201
	v_rcp_f32_e32 v202, v202
	v_rcp_f32_e32 v203, v203
	v_fma_f32 v196, v196, -2.0, 1.0
	v_fma_f32 v197, v197, -2.0, 1.0
	v_fma_f32 v198, v198, -2.0, 1.0
	v_fma_f32 v199, v199, -2.0, 1.0
	v_fma_f32 v200, v200, -2.0, 1.0
	v_fma_f32 v201, v201, -2.0, 1.0
	v_fma_f32 v202, v202, -2.0, 1.0
	v_fma_f32 v203, v203, -2.0, 1.0
	s_mov_b64 exec, s[60:61]

; __device__ __forceinline__ unsigned cvt_pk_bf16(float lo, float hi) { const f32x2_cv v = {lo, hi}; const bf16x2_cv b = __builtin_convertvector(v, bf16x2_cv); return __builtin_bit_cast(unsigned, b); }
; __device__ __forceinline__ float sigm(float x) { return __builtin_amdgcn_rcpf(1.0f + __expf(-x)); }
; __device__ __forceinline__ float tanh_fast(float x) { return 1.0f - 2.0f * __builtin_amdgcn_rcpf(1.0f + __expf(2.0f * x)); }
; __device__ __forceinline__ float lo16(unsigned w) { return __uint_as_float(w << 16); }
; __device__ __forceinline__ float hi16(unsigned w) { return __uint_as_float(w & 0xffff0000u); }
; __device__ void phase_prep(const Ctx& p, int l, LAS unsigned char* lds) {
;     ...
;             for (int rr = 0; rr < 8; ++rr) {
;                 const int r = r8 + rr; const u32x4 w = wrow[rr];
;                 float cur[8], o[8];
;                 cur[0] = lo16(w.x); cur[1] = hi16(w.x); cur[2] = lo16(w.y); cur[3] = hi16(w.y); cur[4] = lo16(w.z); cur[5] = hi16(w.z); cur[6] = lo16(w.w); cur[7] = hi16(w.w);
; #pragma unroll
;                 for (int j = 0; j < 8; ++j) { float x = cur[j] + (prev[j] - cur[j]) * m8[j]; if (fn == 1) x = tanh_fast(x); else if (fn == 2) x = sigm(x); o[j] = x; prev[j] = cur[j]; }
;                 u32x4 q; q.x = cvt_pk_bf16(o[0], o[1]); q.y = cvt_pk_bf16(o[2], o[3]); q.z = cvt_pk_bf16(o[4], o[5]); q.w = cvt_pk_bf16(o[6], o[7]);
;                 *(LAS u32x4*)(MX + (rstart + r) * MXS + c0) = q;
.Lshift_ns3:
	s_nop 0
	v_cvt_pk_bf16_f32 v212, v196, v197
	v_cvt_pk_bf16_f32 v213, v198, v199
	v_cvt_pk_bf16_f32 v214, v200, v201
	v_cvt_pk_bf16_f32 v215, v202, v203
	ds_write_b128 v220, v[212:215] offset:10992
	s_waitcnt vmcnt(11)
	v_lshlrev_b32_e32 v196, 16, v20
	v_and_b32_e32 v197, 0xffff0000, v20
	v_lshlrev_b32_e32 v198, 16, v21
	v_and_b32_e32 v199, 0xffff0000, v21
	v_lshlrev_b32_e32 v200, 16, v22
	v_and_b32_e32 v201, 0xffff0000, v22
	v_lshlrev_b32_e32 v202, 16, v23
	v_and_b32_e32 v203, 0xffff0000, v23
	v_sub_f32_e32 v204, v204, v196
	v_sub_f32_e32 v205, v205, v197
	v_sub_f32_e32 v206, v206, v198
	v_sub_f32_e32 v207, v207, v199
	v_sub_f32_e32 v208, v208, v200
	v_sub_f32_e32 v209, v209, v201
	v_sub_f32_e32 v210, v210, v202
	v_sub_f32_e32 v211, v211, v203
	v_fma_f32 v204, v4, v204, v196
	v_fma_f32 v205, v5, v205, v197
	v_fma_f32 v206, v6, v206, v198
	v_fma_f32 v207, v7, v207, v199
	v_fma_f32 v208, v0, v208, v200
	v_fma_f32 v209, v1, v209, v201
	v_fma_f32 v210, v2, v210, v202
	v_fma_f32 v211, v3, v211, v203
	s_cmp_lg_u64 s[62:63], 0
	s_cbranch_scc0 .Lshift_nt4
	s_mov_b64 exec, s[62:63]
	v_add_f32_e32 v204, v204, v204
	v_add_f32_e32 v205, v205, v205
	v_add_f32_e32 v206, v206, v206
	v_add_f32_e32 v207, v207, v207
	v_add_f32_e32 v208, v208, v208
	v_add_f32_e32 v209, v209, v209
	v_add_f32_e32 v210, v210, v210
	v_add_f32_e32 v211, v211, v211
	v_mul_f32_e32 v204, 0x3fb8aa3b, v204
	v_mul_f32_e32 v205, 0x3fb8aa3b, v205
	v_mul_f32_e32 v206, 0x3fb8aa3b, v206
	v_mul_f32_e32 v207, 0x3fb8aa3b, v207
	v_mul_f32_e32 v208, 0x3fb8aa3b, v208
	v_mul_f32_e32 v209, 0x3fb8aa3b, v209
	v_mul_f32_e32 v210, 0x3fb8aa3b, v210
	v_mul_f32_e32 v211, 0x3fb8aa3b, v211
	v_exp_f32_e32 v204, v204
	v_exp_f32_e32 v205, v205
	v_exp_f32_e32 v206, v206
	v_exp_f32_e32 v207, v207
	v_exp_f32_e32 v208, v208
	v_exp_f32_e32 v209, v209
	v_exp_f32_e32 v210, v210
	v_exp_f32_e32 v211, v211
	v_add_f32_e32 v204, 1.0, v204
	v_add_f32_e32 v205, 1.0, v205
	v_add_f32_e32 v206, 1.0, v206
	v_add_f32_e32 v207, 1.0, v207
	v_add_f32_e32 v208, 1.0, v208
	v_add_f32_e32 v209, 1.0, v209
	v_add_f32_e32 v210, 1.0, v210
	v_add_f32_e32 v211, 1.0, v211
	v_rcp_f32_e32 v204, v204
	v_rcp_f32_e32 v205, v205
	v_rcp_f32_e32 v206, v206
	v_rcp_f32_e32 v207, v207
	v_rcp_f32_e32 v208, v208
	v_rcp_f32_e32 v209, v209
	v_rcp_f32_e32 v210, v210
	v_rcp_f32_e32 v211, v211
	v_fma_f32 v204, v204, -2.0, 1.0
	v_fma_f32 v205, v205, -2.0, 1.0
	v_fma_f32 v206, v206, -2.0, 1.0
	v_fma_f32 v207, v207, -2.0, 1.0
	v_fma_f32 v208, v208, -2.0, 1.0
	v_fma_f32 v209, v209, -2.0, 1.0
	v_fma_f32 v210, v210, -2.0, 1.0
	v_fma_f32 v211, v211, -2.0, 1.0
	s_mov_b64 exec, s[60:61]

; __device__ __forceinline__ unsigned cvt_pk_bf16(float lo, float hi) { const f32x2_cv v = {lo, hi}; const bf16x2_cv b = __builtin_convertvector(v, bf16x2_cv); return __builtin_bit_cast(unsigned, b); }
; __device__ __forceinline__ float sigm(float x) { return __builtin_amdgcn_rcpf(1.0f + __expf(-x)); }
; __device__ __forceinline__ float tanh_fast(float x) { return 1.0f - 2.0f * __builtin_amdgcn_rcpf(1.0f + __expf(2.0f * x)); }
; __device__ __forceinline__ float lo16(unsigned w) { return __uint_as_float(w << 16); }
; __device__ __forceinline__ float hi16(unsigned w) { return __uint_as_float(w & 0xffff0000u); }
; __device__ void phase_prep(const Ctx& p, int l, LAS unsigned char* lds) {
;     ...
;             for (int rr = 0; rr < 8; ++rr) {
;                 const int r = r8 + rr; const u32x4 w = wrow[rr];
;                 float cur[8], o[8];
;                 cur[0] = lo16(w.x); cur[1] = hi16(w.x); cur[2] = lo16(w.y); cur[3] = hi16(w.y); cur[4] = lo16(w.z); cur[5] = hi16(w.z); cur[6] = lo16(w.w); cur[7] = hi16(w.w);
; #pragma unroll
;                 for (int j = 0; j < 8; ++j) { float x = cur[j] + (prev[j] - cur[j]) * m8[j]; if (fn == 1) x = tanh_fast(x); else if (fn == 2) x = sigm(x); o[j] = x; prev[j] = cur[j]; }
;                 u32x4 q; q.x = cvt_pk_bf16(o[0], o[1]); q.y = cvt_pk_bf16(o[2], o[3]); q.z = cvt_pk_bf16(o[4], o[5]); q.w = cvt_pk_bf16(o[6], o[7]);
;                 *(LAS u32x4*)(MX + (rstart + r) * MXS + c0) = q;
.Lshift_ns4:
	s_nop 0
	v_cvt_pk_bf16_f32 v212, v204, v205
	v_cvt_pk_bf16_f32 v213, v206, v207
	v_cvt_pk_bf16_f32 v214, v208, v209
	v_cvt_pk_bf16_f32 v215, v210, v211
	ds_write_b128 v220, v[212:215] offset:14656
	s_waitcnt vmcnt(10)
	v_lshlrev_b32_e32 v204, 16, v16
	v_and_b32_e32 v205, 0xffff0000, v16
	v_lshlrev_b32_e32 v206, 16, v17
	v_and_b32_e32 v207, 0xffff0000, v17
	v_lshlrev_b32_e32 v208, 16, v18
	v_and_b32_e32 v209, 0xffff0000, v18
	v_lshlrev_b32_e32 v210, 16, v19
	v_and_b32_e32 v211, 0xffff0000, v19
	v_sub_f32_e32 v196, v196, v204
	v_sub_f32_e32 v197, v197, v205
	v_sub_f32_e32 v198, v198, v206
	v_sub_f32_e32 v199, v199, v207
	v_sub_f32_e32 v200, v200, v208
	v_sub_f32_e32 v201, v201, v209
	v_sub_f32_e32 v202, v202, v210
	v_sub_f32_e32 v203, v203, v211
	v_fma_f32 v196, v4, v196, v204
	v_fma_f32 v197, v5, v197, v205
	v_fma_f32 v198, v6, v198, v206
	v_fma_f32 v199, v7, v199, v207
	v_fma_f32 v200, v0, v200, v208
	v_fma_f32 v201, v1, v201, v209
	v_fma_f32 v202, v2, v202, v210
	v_fma_f32 v203, v3, v203, v211
	s_cmp_lg_u64 s[62:63], 0
	s_cbranch_scc0 .Lshift_nt5
	s_mov_b64 exec, s[62:63]
	v_add_f32_e32 v196, v196, v196
	v_add_f32_e32 v197, v197, v197
	v_add_f32_e32 v198, v198, v198
	v_add_f32_e32 v199, v199, v199
	v_add_f32_e32 v200, v200, v200
	v_add_f32_e32 v201, v201, v201
	v_add_f32_e32 v202, v202, v202
	v_add_f32_e32 v203, v203, v203
	v_mul_f32_e32 v196, 0x3fb8aa3b, v196
	v_mul_f32_e32 v197, 0x3fb8aa3b, v197
	v_mul_f32_e32 v198, 0x3fb8aa3b, v198
	v_mul_f32_e32 v199, 0x3fb8aa3b, v199
	v_mul_f32_e32 v200, 0x3fb8aa3b, v200
	v_mul_f32_e32 v201, 0x3fb8aa3b, v201
	v_mul_f32_e32 v202, 0x3fb8aa3b, v202
	v_mul_f32_e32 v203, 0x3fb8aa3b, v203
	v_exp_f32_e32 v196, v196
	v_exp_f32_e32 v197, v197
	v_exp_f32_e32 v198, v198
	v_exp_f32_e32 v199, v199
	v_exp_f32_e32 v200, v200
	v_exp_f32_e32 v201, v201
	v_exp_f32_e32 v202, v202
	v_exp_f32_e32 v203, v203
	v_add_f32_e32 v196, 1.0, v196
	v_add_f32_e32 v197, 1.0, v197
	v_add_f32_e32 v198, 1.0, v198
	v_add_f32_e32 v199, 1.0, v199
	v_add_f32_e32 v200, 1.0, v200
	v_add_f32_e32 v201, 1.0, v201
	v_add_f32_e32 v202, 1.0, v202
	v_add_f32_e32 v203, 1.0, v203
	v_rcp_f32_e32 v196, v196
	v_rcp_f32_e32 v197, v197
	v_rcp_f32_e32 v198, v198
	v_rcp_f32_e32 v199, v199
	v_rcp_f32_e32 v200, v200
	v_rcp_f32_e32 v201, v201
	v_rcp_f32_e32 v202, v202
	v_rcp_f32_e32 v203, v203
	v_fma_f32 v196, v196, -2.0, 1.0
	v_fma_f32 v197, v197, -2.0, 1.0
	v_fma_f32 v198, v198, -2.0, 1.0
	v_fma_f32 v199, v199, -2.0, 1.0
	v_fma_f32 v200, v200, -2.0, 1.0
	v_fma_f32 v201, v201, -2.0, 1.0
	v_fma_f32 v202, v202, -2.0, 1.0
	v_fma_f32 v203, v203, -2.0, 1.0
	s_mov_b64 exec, s[60:61]

; __device__ __forceinline__ unsigned cvt_pk_bf16(float lo, float hi) { const f32x2_cv v = {lo, hi}; const bf16x2_cv b = __builtin_convertvector(v, bf16x2_cv); return __builtin_bit_cast(unsigned, b); }
; __device__ __forceinline__ float sigm(float x) { return __builtin_amdgcn_rcpf(1.0f + __expf(-x)); }
; __device__ __forceinline__ float tanh_fast(float x) { return 1.0f - 2.0f * __builtin_amdgcn_rcpf(1.0f + __expf(2.0f * x)); }
; __device__ __forceinline__ float lo16(unsigned w) { return __uint_as_float(w << 16); }
; __device__ __forceinline__ float hi16(unsigned w) { return __uint_as_float(w & 0xffff0000u); }
; __device__ void phase_prep(const Ctx& p, int l, LAS unsigned char* lds) {
;     ...
;             for (int rr = 0; rr < 8; ++rr) {
;                 const int r = r8 + rr; const u32x4 w = wrow[rr];
;                 float cur[8], o[8];
;                 cur[0] = lo16(w.x); cur[1] = hi16(w.x); cur[2] = lo16(w.y); cur[3] = hi16(w.y); cur[4] = lo16(w.z); cur[5] = hi16(w.z); cur[6] = lo16(w.w); cur[7] = hi16(w.w);
; #pragma unroll
;                 for (int j = 0; j < 8; ++j) { float x = cur[j] + (prev[j] - cur[j]) * m8[j]; if (fn == 1) x = tanh_fast(x); else if (fn == 2) x = sigm(x); o[j] = x; prev[j] = cur[j]; }
;                 u32x4 q; q.x = cvt_pk_bf16(o[0], o[1]); q.y = cvt_pk_bf16(o[2], o[3]); q.z = cvt_pk_bf16(o[4], o[5]); q.w = cvt_pk_bf16(o[6], o[7]);
;                 *(LAS u32x4*)(MX + (rstart + r) * MXS + c0) = q;
.Lshift_ns5:
	s_nop 0
	v_cvt_pk_bf16_f32 v212, v196, v197
	v_cvt_pk_bf16_f32 v213, v198, v199
	v_cvt_pk_bf16_f32 v214, v200, v201
	v_cvt_pk_bf16_f32 v215, v202, v203
	ds_write_b128 v220, v[212:215] offset:18320
	s_waitcnt vmcnt(9)
	v_lshlrev_b32_e32 v196, 16, v12
	v_and_b32_e32 v197, 0xffff0000, v12
	v_lshlrev_b32_e32 v198, 16, v13
	v_and_b32_e32 v199, 0xffff0000, v13
	v_lshlrev_b32_e32 v200, 16, v14
	v_and_b32_e32 v201, 0xffff0000, v14
	v_lshlrev_b32_e32 v202, 16, v15
	v_and_b32_e32 v203, 0xffff0000, v15
	v_sub_f32_e32 v204, v204, v196
	v_sub_f32_e32 v205, v205, v197
	v_sub_f32_e32 v206, v206, v198
	v_sub_f32_e32 v207, v207, v199
	v_sub_f32_e32 v208, v208, v200
	v_sub_f32_e32 v209, v209, v201
	v_sub_f32_e32 v210, v210, v202
	v_sub_f32_e32 v211, v211, v203
	v_fma_f32 v204, v4, v204, v196
	v_fma_f32 v205, v5, v205, v197
	v_fma_f32 v206, v6, v206, v198
	v_fma_f32 v207, v7, v207, v199
	v_fma_f32 v208, v0, v208, v200
	v_fma_f32 v209, v1, v209, v201
	v_fma_f32 v210, v2, v210, v202
	v_fma_f32 v211, v3, v211, v203
	s_cmp_lg_u64 s[62:63], 0
	s_cbranch_scc0 .Lshift_nt6
	s_mov_b64 exec, s[62:63]
	v_add_f32_e32 v204, v204, v204
	v_add_f32_e32 v205, v205, v205
	v_add_f32_e32 v206, v206, v206
	v_add_f32_e32 v207, v207, v207
	v_add_f32_e32 v208, v208, v208
	v_add_f32_e32 v209, v209, v209
	v_add_f32_e32 v210, v210, v210
	v_add_f32_e32 v211, v211, v211
	v_mul_f32_e32 v204, 0x3fb8aa3b, v204
	v_mul_f32_e32 v205, 0x3fb8aa3b, v205
	v_mul_f32_e32 v206, 0x3fb8aa3b, v206
	v_mul_f32_e32 v207, 0x3fb8aa3b, v207
	v_mul_f32_e32 v208, 0x3fb8aa3b, v208
	v_mul_f32_e32 v209, 0x3fb8aa3b, v209
	v_mul_f32_e32 v210, 0x3fb8aa3b, v210
	v_mul_f32_e32 v211, 0x3fb8aa3b, v211
	v_exp_f32_e32 v204, v204
	v_exp_f32_e32 v205, v205
	v_exp_f32_e32 v206, v206
	v_exp_f32_e32 v207, v207
	v_exp_f32_e32 v208, v208
	v_exp_f32_e32 v209, v209
	v_exp_f32_e32 v210, v210
	v_exp_f32_e32 v211, v211
	v_add_f32_e32 v204, 1.0, v204
	v_add_f32_e32 v205, 1.0, v205
	v_add_f32_e32 v206, 1.0, v206
	v_add_f32_e32 v207, 1.0, v207
	v_add_f32_e32 v208, 1.0, v208
	v_add_f32_e32 v209, 1.0, v209
	v_add_f32_e32 v210, 1.0, v210
	v_add_f32_e32 v211, 1.0, v211
	v_rcp_f32_e32 v204, v204
	v_rcp_f32_e32 v205, v205
	v_rcp_f32_e32 v206, v206
	v_rcp_f32_e32 v207, v207
	v_rcp_f32_e32 v208, v208
	v_rcp_f32_e32 v209, v209
	v_rcp_f32_e32 v210, v210
	v_rcp_f32_e32 v211, v211
	v_fma_f32 v204, v204, -2.0, 1.0
	v_fma_f32 v205, v205, -2.0, 1.0
	v_fma_f32 v206, v206, -2.0, 1.0
	v_fma_f32 v207, v207, -2.0, 1.0
	v_fma_f32 v208, v208, -2.0, 1.0
	v_fma_f32 v209, v209, -2.0, 1.0
	v_fma_f32 v210, v210, -2.0, 1.0
	v_fma_f32 v211, v211, -2.0, 1.0
	s_mov_b64 exec, s[60:61]

; __device__ __forceinline__ unsigned cvt_pk_bf16(float lo, float hi) { const f32x2_cv v = {lo, hi}; const bf16x2_cv b = __builtin_convertvector(v, bf16x2_cv); return __builtin_bit_cast(unsigned, b); }
; __device__ __forceinline__ float sigm(float x) { return __builtin_amdgcn_rcpf(1.0f + __expf(-x)); }
; __device__ __forceinline__ float tanh_fast(float x) { return 1.0f - 2.0f * __builtin_amdgcn_rcpf(1.0f + __expf(2.0f * x)); }
; __device__ __forceinline__ float lo16(unsigned w) { return __uint_as_float(w << 16); }
; __device__ __forceinline__ float hi16(unsigned w) { return __uint_as_float(w & 0xffff0000u); }
; __device__ void phase_prep(const Ctx& p, int l, LAS unsigned char* lds) {
;     ...
;             for (int rr = 0; rr < 8; ++rr) {
;                 const int r = r8 + rr; const u32x4 w = wrow[rr];
;                 float cur[8], o[8];
;                 cur[0] = lo16(w.x); cur[1] = hi16(w.x); cur[2] = lo16(w.y); cur[3] = hi16(w.y); cur[4] = lo16(w.z); cur[5] = hi16(w.z); cur[6] = lo16(w.w); cur[7] = hi16(w.w);
; #pragma unroll
;                 for (int j = 0; j < 8; ++j) { float x = cur[j] + (prev[j] - cur[j]) * m8[j]; if (fn == 1) x = tanh_fast(x); else if (fn == 2) x = sigm(x); o[j] = x; prev[j] = cur[j]; }
;                 u32x4 q; q.x = cvt_pk_bf16(o[0], o[1]); q.y = cvt_pk_bf16(o[2], o[3]); q.z = cvt_pk_bf16(o[4], o[5]); q.w = cvt_pk_bf16(o[6], o[7]);
;                 *(LAS u32x4*)(MX + (rstart + r) * MXS + c0) = q;
.Lshift_ns6:
	s_nop 0
	v_cvt_pk_bf16_f32 v212, v204, v205
	v_cvt_pk_bf16_f32 v213, v206, v207
	v_cvt_pk_bf16_f32 v214, v208, v209
	v_cvt_pk_bf16_f32 v215, v210, v211
	ds_write_b128 v220, v[212:215] offset:21984
	s_waitcnt vmcnt(8)
	v_lshlrev_b32_e32 v40, 16, v8
	v_and_b32_e32 v41, 0xffff0000, v8
	v_lshlrev_b32_e32 v42, 16, v9
	v_and_b32_e32 v43, 0xffff0000, v9
	v_lshlrev_b32_e32 v36, 16, v10
	v_and_b32_e32 v37, 0xffff0000, v10
	v_lshlrev_b32_e32 v38, 16, v11
	v_and_b32_e32 v39, 0xffff0000, v11
	v_sub_f32_e32 v196, v196, v40
	v_sub_f32_e32 v197, v197, v41
	v_sub_f32_e32 v198, v198, v42
	v_sub_f32_e32 v199, v199, v43
	v_sub_f32_e32 v200, v200, v36
	v_sub_f32_e32 v201, v201, v37
	v_sub_f32_e32 v202, v202, v38
	v_sub_f32_e32 v203, v203, v39
	v_fma_f32 v196, v4, v196, v40
	v_fma_f32 v197, v5, v197, v41
	v_fma_f32 v198, v6, v198, v42
	v_fma_f32 v199, v7, v199, v43
	v_fma_f32 v200, v0, v200, v36
	v_fma_f32 v201, v1, v201, v37
	v_fma_f32 v202, v2, v202, v38
	v_fma_f32 v203, v3, v203, v39
	s_cmp_lg_u64 s[62:63], 0
	s_cbranch_scc0 .Lshift_nt7
	s_mov_b64 exec, s[62:63]
	v_add_f32_e32 v196, v196, v196
	v_add_f32_e32 v197, v197, v197
	v_add_f32_e32 v198, v198, v198
	v_add_f32_e32 v199, v199, v199
	v_add_f32_e32 v200, v200, v200
	v_add_f32_e32 v201, v201, v201
	v_add_f32_e32 v202, v202, v202
	v_add_f32_e32 v203, v203, v203
	v_mul_f32_e32 v196, 0x3fb8aa3b, v196
	v_mul_f32_e32 v197, 0x3fb8aa3b, v197
	v_mul_f32_e32 v198, 0x3fb8aa3b, v198
	v_mul_f32_e32 v199, 0x3fb8aa3b, v199
	v_mul_f32_e32 v200, 0x3fb8aa3b, v200
	v_mul_f32_e32 v201, 0x3fb8aa3b, v201
	v_mul_f32_e32 v202, 0x3fb8aa3b, v202
	v_mul_f32_e32 v203, 0x3fb8aa3b, v203
	v_exp_f32_e32 v196, v196
	v_exp_f32_e32 v197, v197
	v_exp_f32_e32 v198, v198
	v_exp_f32_e32 v199, v199
	v_exp_f32_e32 v200, v200
	v_exp_f32_e32 v201, v201
	v_exp_f32_e32 v202, v202
	v_exp_f32_e32 v203, v203
	v_add_f32_e32 v196, 1.0, v196
	v_add_f32_e32 v197, 1.0, v197
	v_add_f32_e32 v198, 1.0, v198
	v_add_f32_e32 v199, 1.0, v199
	v_add_f32_e32 v200, 1.0, v200
	v_add_f32_e32 v201, 1.0, v201
	v_add_f32_e32 v202, 1.0, v202
	v_add_f32_e32 v203, 1.0, v203
	v_rcp_f32_e32 v196, v196
	v_rcp_f32_e32 v197, v197
	v_rcp_f32_e32 v198, v198
	v_rcp_f32_e32 v199, v199
	v_rcp_f32_e32 v200, v200
	v_rcp_f32_e32 v201, v201
	v_rcp_f32_e32 v202, v202
	v_rcp_f32_e32 v203, v203
	v_fma_f32 v196, v196, -2.0, 1.0
	v_fma_f32 v197, v197, -2.0, 1.0
	v_fma_f32 v198, v198, -2.0, 1.0
	v_fma_f32 v199, v199, -2.0, 1.0
	v_fma_f32 v200, v200, -2.0, 1.0
	v_fma_f32 v201, v201, -2.0, 1.0
	v_fma_f32 v202, v202, -2.0, 1.0
	v_fma_f32 v203, v203, -2.0, 1.0
	s_mov_b64 exec, s[60:61]
